# baseline (speedup 1.0000x reference)
; #define LAS __attribute__((address_space(3)))
; __device__ __forceinline__ void build_rtab(unsigned char* ws, LAS float* rtab, int pm) {
;     int t = threadIdx.x; asm volatile("" : "+v"(t));
;     if (t < 256) { const float* sp = (const float*)(ws + WS_SSQ) + (size_t)(pm * 256 + t) * 32; float a = 0.f;
; #pragma unroll
;         for (int j = 0; j < 8; ++j) { const f32x4 v = *(const f32x4*)(sp + 4 * j); a += (v[0] + v[1]) + (v[2] + v[3]); }
;         rtab[t] = __builtin_amdgcn_rsqf(a * (1.0f / DM) + RMS_EPS); }
.LBB0_68:
	v_readlane_b32 s8, v255, 33
	v_mov_b32_e32 v128, v210
	v_mov_b32_e32 v136, v211
	s_mov_b64 s[6:7], s[94:95]
	v_mov_b32_e32 v129, s8
	ds_read_b32 v129, v129
	s_lshl_b32 s41, s22, 8
	s_waitcnt lgkmcnt(0)
	v_cmp_eq_u32_e32 vcc, s22, v129
	s_cbranch_vccnz .LBB0_74
	s_waitcnt lgkmcnt(0)
	v_mov_b32_e32 v129, v230
	s_movk_i32 s8, 0x100
	s_barrier
	s_nop 0
	v_cmp_gt_i32_e32 vcc, s8, v129
	s_and_saveexec_b64 s[8:9], vcc
	s_cbranch_execz .LBB0_71
	v_add_u32_e32 v130, s41, v129
	v_ashrrev_i32_e32 v131, 31, v130
	v_lshlrev_b64 v[130:131], 7, v[130:131]
	v_lshl_add_u64 v[130:131], s[6:7], 0, v[130:131]
	s_mov_b64 s[74:75], 0x1a400000
	v_lshl_add_u64 v[134:135], v[130:131], 0, s[74:75]
	v_add_co_u32_e32 v130, vcc, 0x1a400000, v130
	v_lshl_add_u32 v129, v129, 2, 0
	s_nop 0
	v_addc_co_u32_e32 v131, vcc, 0, v131, vcc
	flat_load_dwordx4 v[130:133], v[130:131]
	s_nop 0
	flat_load_dwordx4 v[138:141], v[134:135] offset:16
	flat_load_dwordx4 v[178:181], v[134:135] offset:32
	flat_load_dwordx4 v[184:187], v[134:135] offset:48
	v_add_u32_e32 v129, 0x22100, v129
	s_waitcnt vmcnt(0) lgkmcnt(0)
	v_mov_b32_e32 v142, v130
	v_mov_b32_e32 v143, v138
	v_mov_b32_e32 v138, v131
	v_pk_add_f32 v[130:131], v[142:143], v[138:139]
	v_mov_b32_e32 v138, v132
	v_mov_b32_e32 v139, v140
	v_mov_b32_e32 v140, v133
	v_pk_add_f32 v[132:133], v[138:139], v[140:141]
	s_nop 0
	v_pk_add_f32 v[130:131], v[130:131], v[132:133]
	s_nop 0
	v_add_f32_e32 v130, 0, v130
	v_add_f32_e32 v138, v130, v131
	v_mov_b32_e32 v130, v178
	v_mov_b32_e32 v131, v179
	v_mov_b32_e32 v132, v180
	v_mov_b32_e32 v133, v181
	v_mov_b32_e32 v140, v131
	v_mov_b32_e32 v141, v132
	v_mov_b32_e32 v131, v133
	v_pk_add_f32 v[130:131], v[140:141], v[130:131]
	s_nop 0
	v_pk_add_f32 v[140:141], v[130:131], v[130:131] op_sel:[0,1] op_sel_hi:[1,0]
	v_mov_b32_e32 v130, v184
	v_mov_b32_e32 v131, v185
	v_mov_b32_e32 v132, v186
	v_mov_b32_e32 v133, v187
	v_add_f32_e32 v142, v130, v131
	v_add_f32_e32 v144, v132, v133
	v_add_f32_e32 v138, v138, v140
	v_add_f32_e32 v142, v142, v144
	flat_load_dwordx4 v[130:133], v[134:135] offset:64
	flat_load_dwordx4 v[178:181], v[134:135] offset:80
	flat_load_dwordx4 v[184:187], v[134:135] offset:96
	v_add_f32_e32 v142, v138, v142
	flat_load_dwordx4 v[138:141], v[134:135] offset:112
	s_waitcnt vmcnt(0) lgkmcnt(0)
	v_add_f32_e32 v143, v130, v131
	v_add_f32_e32 v144, v132, v133
	v_add_f32_e32 v143, v143, v144
	v_add_f32_e32 v142, v142, v143
	v_add_f32_e32 v143, v178, v179
	v_add_f32_e32 v144, v180, v181
	v_add_f32_e32 v143, v143, v144
	v_add_f32_e32 v142, v142, v143
	v_add_f32_e32 v143, v184, v185
	v_add_f32_e32 v144, v186, v187
	v_add_f32_e32 v143, v143, v144
	v_add_f32_e32 v142, v142, v143
	v_add_f32_e32 v143, v138, v139
	v_add_f32_e32 v144, v140, v141
	v_add_f32_e32 v143, v143, v144
	v_add_f32_e32 v130, v142, v143
	v_fmamk_f32 v130, v130, 0x3a000000, v232
	v_rsq_f32_e32 v130, v130
	ds_write_b32 v129, v130
